# v96 + shift/mask fast path in the GEMM tile decode + XCD barrier moved ahead of the SwiGLU context tiles (down-projection starts earlier on single-context-tile workgroups)
# speedup vs baseline: 1.0040x; 1.0040x over previous
;     DI bool next(int i, Unit& u) const {
;         const long L = (long)i * G + c; if (L >= nwg) return false;
;         if (fmode) { const int w = (int)L; u.pz = 0;
;             if (w < 272) { const int b = w / 17, r = w % 17; if (r < 9) { u.pm = 3; u.pn = b * 16 + r; } else { u.pm = 4; u.pn = b * 16 + r - 1; } }
;             else { const int cq = w - 272; u.pm = 3 + (cq & 1); u.pn = TL / 256 + (cq >> 1); }
;             return true; }
;         int wgid = (int)L; { const int q = nwg / NXCD, r = nwg % NXCD, xcd = wgid % NXCD, off = wgid / NXCD; wgid = (xcd < r ? xcd * (q + 1) : r * (q + 1) + (xcd - r) * q) + off; }
;         u.pz = wgid / per; const int w = wgid % per;
;         const int nig = WGM * nN, gid = w / nig, fm = gid * WGM, gsz = (nM - fm) < WGM ? (nM - fm) : WGM;
;         u.pm = pm0 + fm + ((w % nig) % gsz); u.pn = (w % nig) / gsz; return true;
;     }
.LBB0_459:
	s_add_i32 s49, s49, 1
	s_mul_i32 s4, s49, s46
	s_mul_hi_u32 s5, s49, s3
	s_add_i32 s5, s5, s4
	s_mul_i32 s4, s49, s3
	s_add_u32 s4, s4, s2
	s_addc_u32 s5, s5, s19
	v_mov_b64_e32 v[2:3], s[76:77]
	v_cmp_ge_i64_e32 vcc, s[4:5], v[2:3]
	v_cmp_lt_i64_e64 s[6:7], s[4:5], v[2:3]
	s_cbranch_vccnz .LBB0_461
	s_ashr_i32 s5, s4, 31
	s_lshr_b32 s5, s5, 29
	s_add_i32 s5, s4, s5
	s_ashr_i32 s33, s5, 3
	s_and_b32 s5, s5, -8
	s_sub_i32 s4, s4, s5
	s_lshr_b32 s5, s4, 31
	s_or_b32 s5, s18, s5
	s_mul_i32 s4, s5, s4
	s_add_i32 s4, s4, s33
	s_abs_i32 s33, s4
	s_mul_hi_u32 s52, s33, s36
	s_mul_i32 s53, s52, s34
	s_ashr_i32 s5, s4, 31
	s_sub_i32 s33, s33, s53
	s_xor_b32 s5, s5, s28
	s_add_i32 s53, s52, 1
	s_sub_i32 s81, s33, s34
	s_cmp_ge_u32 s33, s34
	s_cselect_b32 s52, s53, s52
	s_cselect_b32 s33, s81, s33
	s_add_i32 s53, s52, 1
	s_cmp_ge_u32 s33, s34
	s_cselect_b32 s33, s53, s52
	s_xor_b32 s33, s33, s5
	s_sub_i32 s81, s33, s5
	s_mul_i32 s5, s81, s10
	s_sub_i32 s4, s4, s5
	s_abs_i32 s33, s4
	s_mul_hi_u32 s52, s33, s51
	s_mul_i32 s53, s52, s48
	s_ashr_i32 s5, s4, 31
	s_sub_i32 s33, s33, s53
	s_xor_b32 s5, s5, s47
	s_add_i32 s53, s52, 1
	s_sub_i32 s88, s33, s48
	s_cmp_ge_u32 s33, s48
	s_cselect_b32 s52, s53, s52
	s_cselect_b32 s33, s88, s33
	s_add_i32 s53, s52, 1
	s_cmp_ge_u32 s33, s48
	s_cselect_b32 s33, s53, s52
	s_xor_b32 s33, s33, s5
	s_sub_i32 s5, s33, s5
	s_lshl_b32 s52, s5, 2
	s_sub_i32 s33, s16, s52
	s_min_i32 s53, s33, 4
	s_mul_i32 s5, s5, s11
	s_sub_i32 s4, s4, s5
	s_cmp_eq_u32 s53, 4
	s_cbranch_scc0 .Lfd_slow_466
	s_lshr_b32 s33, s4, 2
	s_and_b32 s4, s4, 3
	s_add_i32 s52, s4, s52
	s_branch .LBB0_461
.Lfd_slow_466:
	s_abs_i32 s33, s53
	v_cvt_f32_u32_e32 v2, s33
	s_sub_i32 s89, 0, s33
	v_rcp_iflag_f32_e32 v2, v2
	s_abs_i32 s88, s4
	s_xor_b32 s5, s4, s53
	s_ashr_i32 s5, s5, 31
	v_mul_f32_e32 v2, 0x4f7ffffe, v2
	v_cvt_u32_f32_e32 v2, v2
	s_nop 0
	v_readfirstlane_b32 s94, v2
	s_mul_i32 s89, s89, s94
	s_mul_hi_u32 s89, s94, s89
	s_add_i32 s94, s94, s89
	s_mul_hi_u32 s89, s88, s94
	s_mul_i32 s94, s89, s33
	s_sub_i32 s88, s88, s94
	s_add_i32 s94, s89, 1
	s_sub_i32 s95, s88, s33
	s_cmp_ge_u32 s88, s33
	s_cselect_b32 s89, s94, s89
	s_cselect_b32 s88, s95, s88
	s_add_i32 s94, s89, 1
	s_cmp_ge_u32 s88, s33
	s_cselect_b32 s33, s94, s89
	s_xor_b32 s33, s33, s5
	s_sub_i32 s33, s33, s5
	s_mul_i32 s5, s33, s53
	s_sub_i32 s4, s4, s5
	s_add_i32 s52, s4, s52

;     DI bool next(int i, Unit& u) const {
;         const long L = (long)i * G + c; if (L >= nwg) return false;
;         if (fmode) { const int w = (int)L; u.pz = 0;
;             if (w < 272) { const int b = w / 17, r = w % 17; if (r < 9) { u.pm = 3; u.pn = b * 16 + r; } else { u.pm = 4; u.pn = b * 16 + r - 1; } }
;             else { const int cq = w - 272; u.pm = 3 + (cq & 1); u.pn = TL / 256 + (cq >> 1); }
;             return true; }
;         int wgid = (int)L; { const int q = nwg / NXCD, r = nwg % NXCD, xcd = wgid % NXCD, off = wgid / NXCD; wgid = (xcd < r ? xcd * (q + 1) : r * (q + 1) + (xcd - r) * q) + off; }
;         u.pz = wgid / per; const int w = wgid % per;
;         const int nig = WGM * nN, gid = w / nig, fm = gid * WGM, gsz = (nM - fm) < WGM ? (nM - fm) : WGM;
;         u.pm = pm0 + fm + ((w % nig) % gsz); u.pn = (w % nig) / gsz; return true;
;     }
.LBB0_486:
	s_add_i32 s17, s17, 1
	s_mul_i32 s4, s17, s16
	s_mul_hi_u32 s5, s17, s3
	s_add_i32 s5, s5, s4
	s_mul_i32 s4, s17, s3
	s_add_u32 s4, s4, s2
	s_addc_u32 s5, s5, s34
	v_mov_b64_e32 v[2:3], s[74:75]
	v_cmp_ge_i64_e32 vcc, s[4:5], v[2:3]
	v_cmp_lt_i64_e64 s[6:7], s[4:5], v[2:3]
	s_cbranch_vccnz .LBB0_488
	s_ashr_i32 s5, s4, 31
	s_lshr_b32 s5, s5, 29
	s_add_i32 s5, s4, s5
	s_ashr_i32 s18, s5, 3
	s_and_b32 s5, s5, -8
	s_sub_i32 s4, s4, s5
	s_lshr_b32 s5, s4, 31
	s_or_b32 s5, s11, s5
	s_mul_i32 s4, s5, s4
	s_add_i32 s4, s4, s18
	s_ashr_i32 s5, s4, 31
	s_abs_i32 s4, s4
	s_mul_hi_u32 s18, s4, s43
	s_mul_i32 s18, s18, s74
	s_sub_i32 s4, s4, s18
	s_sub_i32 s18, s4, s74
	s_cmp_ge_u32 s4, s74
	s_cselect_b32 s4, s18, s4
	s_sub_i32 s18, s4, s74
	s_cmp_ge_u32 s4, s74
	s_cselect_b32 s4, s18, s4
	s_xor_b32 s4, s4, s5
	s_sub_i32 s4, s4, s5
	s_ashr_i32 s5, s4, 31
	s_lshr_b32 s5, s5, 28
	s_add_i32 s5, s4, s5
	s_ashr_i32 s18, s5, 4
	s_lshl_b32 s19, s18, 2
	s_sub_i32 s18, s42, s19
	s_min_i32 s30, s18, 4
	s_and_b32 s5, s5, -16
	s_sub_i32 s4, s4, s5
	s_cmp_eq_u32 s30, 4
	s_cbranch_scc0 .Lfd_slow_493
	s_lshr_b32 s18, s4, 2
	s_and_b32 s4, s4, 3
	s_add_i32 s19, s19, s4
	s_branch .LBB0_488
.Lfd_slow_493:
	s_abs_i32 s18, s30
	v_cvt_f32_u32_e32 v2, s18
	s_sub_i32 s33, 0, s18
	v_rcp_iflag_f32_e32 v2, v2
	s_abs_i32 s5, s4
	s_xor_b32 s31, s4, s30
	s_ashr_i32 s31, s31, 31
	v_mul_f32_e32 v2, 0x4f7ffffe, v2
	v_cvt_u32_f32_e32 v2, v2
	s_nop 0
	v_readfirstlane_b32 s40, v2
	s_mul_i32 s33, s33, s40
	s_mul_hi_u32 s33, s40, s33
	s_add_i32 s40, s40, s33
	s_mul_hi_u32 s33, s5, s40
	s_mul_i32 s40, s33, s18
	s_sub_i32 s5, s5, s40
	s_add_i32 s41, s33, 1
	s_sub_i32 s40, s5, s18
	s_cmp_ge_u32 s5, s18
	s_cselect_b32 s33, s41, s33
	s_cselect_b32 s5, s40, s5
	s_add_i32 s40, s33, 1
	s_cmp_ge_u32 s5, s18
	s_cselect_b32 s5, s40, s33
	s_xor_b32 s5, s5, s31
	s_sub_i32 s18, s5, s31
	s_mul_i32 s5, s18, s30
	s_sub_i32 s4, s4, s5
	s_add_i32 s19, s19, s4

;     DI bool next(int i, Unit& u) const {
;         const long L = (long)i * G + c; if (L >= nwg) return false;
;         if (fmode) { const int w = (int)L; u.pz = 0;
;             if (w < 272) { const int b = w / 17, r = w % 17; if (r < 9) { u.pm = 3; u.pn = b * 16 + r; } else { u.pm = 4; u.pn = b * 16 + r - 1; } }
;             else { const int cq = w - 272; u.pm = 3 + (cq & 1); u.pn = TL / 256 + (cq >> 1); }
;             return true; }
;         int wgid = (int)L; { const int q = nwg / NXCD, r = nwg % NXCD, xcd = wgid % NXCD, off = wgid / NXCD; wgid = (xcd < r ? xcd * (q + 1) : r * (q + 1) + (xcd - r) * q) + off; }
;         u.pz = wgid / per; const int w = wgid % per;
;         const int nig = WGM * nN, gid = w / nig, fm = gid * WGM, gsz = (nM - fm) < WGM ? (nM - fm) : WGM;
;         u.pm = pm0 + fm + ((w % nig) % gsz); u.pn = (w % nig) / gsz; return true;
;     }
.LBB0_510:
	s_add_i32 s37, s37, 1
	s_mul_i32 s4, s37, s31
	s_mul_hi_u32 s5, s37, s3
	s_add_i32 s5, s5, s4
	s_mul_i32 s4, s37, s3
	s_add_u32 s68, s4, s2
	s_addc_u32 s69, s5, s18
	v_mov_b64_e32 v[2:3], s[20:21]
	v_cmp_ge_i64_e32 vcc, s[68:69], v[2:3]
	v_cmp_lt_i64_e64 s[4:5], s[68:69], v[2:3]
	s_cbranch_vccnz .LBB0_512
	s_ashr_i32 s39, s68, 31
	s_lshr_b32 s39, s39, 29
	s_add_i32 s39, s68, s39
	s_ashr_i32 s40, s39, 3
	s_and_b32 s39, s39, -8
	s_sub_i32 s39, s68, s39
	s_lshr_b32 s41, s39, 31
	s_or_b32 s41, s16, s41
	s_mul_i32 s39, s41, s39
	s_add_i32 s39, s39, s40
	s_ashr_i32 s40, s39, 31
	s_abs_i32 s39, s39
	s_mul_hi_u32 s41, s39, s19
	s_mul_i32 s41, s41, s20
	s_sub_i32 s39, s39, s41
	s_sub_i32 s41, s39, s20
	s_cmp_ge_u32 s39, s20
	s_cselect_b32 s39, s41, s39
	s_sub_i32 s41, s39, s20
	s_cmp_ge_u32 s39, s20
	s_cselect_b32 s39, s41, s39
	s_xor_b32 s39, s39, s40
	s_sub_i32 s39, s39, s40
	s_mul_hi_i32 s40, s39, 0x2e8ba2e9
	s_lshr_b32 s41, s40, 31
	s_ashr_i32 s40, s40, 4
	s_add_i32 s40, s40, s41
	s_lshl_b32 s41, s40, 2
	s_sub_i32 s43, s42, s41
	s_min_i32 s43, s43, 4
	s_mulk_i32 s40, 0x58
	s_sub_i32 s39, s39, s40
	s_cmp_eq_u32 s43, 4
	s_cbranch_scc0 .Lfd_slow_513
	s_lshr_b32 s64, s39, 2
	s_and_b32 s39, s39, 3
	s_add_i32 s66, s41, s39
	s_branch .LBB0_512
.Lfd_slow_513:
	s_abs_i32 s45, s43
	v_cvt_f32_u32_e32 v2, s45
	s_sub_i32 s47, 0, s45
	v_rcp_iflag_f32_e32 v2, v2
	s_abs_i32 s40, s39
	s_xor_b32 s46, s39, s43
	s_ashr_i32 s46, s46, 31
	v_mul_f32_e32 v2, 0x4f7ffffe, v2
	v_cvt_u32_f32_e32 v2, v2
	s_nop 0
	v_readfirstlane_b32 s48, v2
	s_mul_i32 s47, s47, s48
	s_mul_hi_u32 s47, s48, s47
	s_add_i32 s48, s48, s47
	s_mul_hi_u32 s47, s40, s48
	s_mul_i32 s48, s47, s45
	s_sub_i32 s40, s40, s48
	s_add_i32 s48, s47, 1
	s_sub_i32 s49, s40, s45
	s_cmp_ge_u32 s40, s45
	s_cselect_b32 s47, s48, s47
	s_cselect_b32 s40, s49, s40
	s_add_i32 s48, s47, 1
	s_cmp_ge_u32 s40, s45
	s_cselect_b32 s40, s48, s47
	s_xor_b32 s40, s40, s46
	s_sub_i32 s64, s40, s46
	s_mul_i32 s40, s64, s43
	s_sub_i32 s39, s39, s40
	s_add_i32 s66, s41, s39

; DI void grid_barrier(unsigned* cnt, unsigned target) {
;     asm volatile("s_waitcnt vmcnt(0) lgkmcnt(0)" ::: "memory");
;     __syncthreads();
;     if (threadIdx.x == 0) {
;         __builtin_amdgcn_fence(__ATOMIC_RELEASE, "agent");
;         asm volatile("s_waitcnt vmcnt(0)" ::: "memory");
;         __hip_atomic_fetch_add(cnt, 1u, __ATOMIC_RELAXED, __HIP_MEMORY_SCOPE_AGENT);
;         while (__hip_atomic_load(cnt, __ATOMIC_RELAXED, __HIP_MEMORY_SCOPE_AGENT) < target) __builtin_amdgcn_s_sleep(2);
;         __builtin_amdgcn_fence(__ATOMIC_ACQUIRE, "agent");
;         asm volatile("s_waitcnt vmcnt(0)" ::: "memory");
;     }
;     __syncthreads();
; }
.Lli_S:
.Llb_S:
	s_mov_b64 exec, s[4:5]
	s_barrier
	v_readlane_b32 s10, v255, 61
	s_lshl_b32 s10, s10, 6
	s_mov_b64 s[4:5], exec
	v_readlane_b32 s6, v255, 3
	v_readlane_b32 s7, v255, 4
	s_and_b64 s[6:7], s[4:5], s[6:7]
	s_mov_b64 exec, s[6:7]
	s_cbranch_execz .Lwd_C
	v_readlane_b32 s2, v255, 0
	s_bfe_u32 s2, s2, 0x20001
	s_lshl_b32 s2, s2, 2
	s_add_u32 s8, s14, s2
	s_addc_u32 s9, s15, 0
